# differential-attention V tensor stored so each V LDS-DMA piece covers 8 full lines (in-proj epilogue addresses + attention-C V source offsets)
# baseline (speedup 1.0000x reference)
;     __device__ __forceinline__ void operator()(const pg8::f32x4 (&acc)[2][2][4][2], const pg8::Unit& u, int wr, int wc, int fr, int fq) const {
;     ...
;         bool normed, keyrow; const float* gain = qn_a; float scale = 1.f; bf16_t* dbase; int dpitch, dcol, nh = 1, hidx = 0;
;         if (pn == 0) { normed = true; gain = qn_a; scale = attn_body::C2; dbase = qa; dpitch = 256; keyrow = false; dcol = wc * 64; }
;         else if (pn == 1) { keyrow = true; dpitch = 64; nh = 2; dcol = 0; if (wc < 2) { normed = true; gain = kn_a; dbase = ka; hidx = wc; } else { normed = false; dbase = va; hidx = wc - 2; } }
;         else if (pn < 5) { normed = false; dbase = hyr; dpitch = 0; keyrow = false; dcol = (pn - 2) * 256 + wc * 64; }
;         else if (pn < 7) { normed = true; gain = qn_d; scale = attn_body::C2; dbase = qd; dpitch = 512; keyrow = false; dcol = ((pn - 5) * 4 + wc) * 64; }
;         else if (pn < 9) { normed = true; gain = kn_d; dbase = kd; dpitch = 64; keyrow = true; nh = 8; hidx = (pn - 7) * 4 + wc; dcol = 0; }
;         else { normed = false; dbase = vd; dpitch = 128; keyrow = true; nh = 4; hidx = (pn - 9) * 2 + (wc >> 1); dcol = (wc & 1) * 64; }
;         pg8::f32x4 gg[2][2];
; #pragma unroll
;         for (int bj = 0; bj < 2; ++bj)
; #pragma unroll
;             for (int n = 0; n < 2; ++n) gg[bj][n] = *(const pg8::f32x4*)(gain + 32 * bj + 8 * fq + 4 * n);
.LBB0_301:
	s_cmp_lg_u64 s[44:45], 0
	s_cselect_b32 s100, 0x70, 0
	s_cmp_eq_u32 s94, 64
	s_cselect_b32 s100, s100, 0
	s_cmp_eq_u32 s94, 0x80
	s_cselect_b32 s100, 0x80, s100
	s_cselect_b32 s101, 64, 0
	v_mov_b32_e32 v246, s100
	v_mul_u32_u24_e32 v246, 36, v246
	v_mov_b32_e32 v247, s101
	v_mad_u32_u24 v246, v247, 55, v246
	v_mov_b32_e32 v247, 0
	v_lshlrev_b32_e32 v52, 2, v152
	global_load_dwordx4 v[56:59], v52, s[92:93] offset:16
	global_load_dwordx4 v[60:63], v52, s[92:93]
	global_load_dwordx4 v[48:51], v52, s[92:93] offset:144
	s_nop 0
	global_load_dwordx4 v[52:55], v52, s[92:93] offset:128
	s_lshl_b32 s70, s40, 8
	s_add_i32 s70, s70, s60
	s_xor_b64 s[92:93], s[66:67], -1
	v_or_b32_e32 v162, s70, v153
	s_mov_b64 s[4:5], -1
	v_cmp_gt_i32_e64 s[40:41], s97, v162
	s_and_b64 vcc, exec, s[92:93]
	s_cbranch_vccz .LBB0_303
	v_ashrrev_i32_e32 v163, 31, v162
	s_mov_b64 s[4:5], 0

;     __device__ __forceinline__ void operator()(const pg8::f32x4 (&acc)[2][2][4][2], const pg8::Unit& u, int wr, int wc, int fr, int fq) const {
;     ...
;                 bf16_t* dp = dbase + drow * dpitch + dcol + 8 * fq;
;                 float rinv = 1.f;
;                 if (normed) { float ss = 0.f;
; #pragma unroll
;                     for (int bj = 0; bj < 2; ++bj)
; #pragma unroll
;                         for (int n = 0; n < 2; ++n) { const pg8::f32x4 x = acc[ai][bj][m][n]; ss += (x[0] * x[0] + x[1] * x[1]) + (x[2] * x[2] + x[3] * x[3]); }
;                     ss = xrow_sum(ss);
;                     rinv = scale * __builtin_amdgcn_rsqf(ss * (1.0f / 64.0f) + EPSF); }
.LBB0_305:
	s_add_i32 s4, s38, -2
	s_cmp_gt_u32 s4, 2
	s_cselect_b64 s[66:67], -1, 0
	s_ashr_i32 s43, s42, 31
	s_lshl_b64 s[4:5], s[42:43], 1
	s_add_u32 s4, s14, s4
	s_addc_u32 s5, s15, s5
	v_cndmask_b32_e64 v164, 0, 1, s[44:45]
	v_lshl_add_u64 v[160:161], s[4:5], 0, v[208:209]
	v_mbcnt_lo_u32_b32 v244, -1, 0
	v_mbcnt_hi_u32_b32 v244, -1, v244
	v_lshrrev_b32_e32 v244, 4, v244
	v_mul_u32_u24_e32 v244, 9, v244
	v_mul_u32_u24_e32 v244, s100, v244
	v_bfe_u32 v245, s100, 4, 1
	v_mul_u32_u24_e32 v244, v245, v244
	v_mov_b32_e32 v245, 0
	v_lshl_add_u64 v[160:161], v[160:161], 0, v[244:245]
	s_mov_b64 s[4:5], -1
	s_and_b64 vcc, exec, s[66:67]
	v_cmp_ne_u32_e64 s[38:39], 1, v164
	s_cbranch_vccz .LBB0_317
	s_and_b64 vcc, exec, s[38:39]
	v_mov_b32_e32 v164, 1.0
	s_cbranch_vccnz .LBB0_308
	v_mul_f32_e32 v164, v141, v141
	v_mul_f32_e32 v165, v143, v143
	v_fmac_f32_e32 v164, v140, v140
	v_fmac_f32_e32 v165, v142, v142
	v_add_f32_e32 v164, v164, v165
	v_mul_f32_e32 v165, v137, v137
	v_mul_f32_e32 v166, v139, v139
	v_fmac_f32_e32 v165, v136, v136
	v_fmac_f32_e32 v166, v138, v138
	v_add_f32_e32 v165, v165, v166
	v_add_f32_e32 v164, v164, v165
	v_mul_f32_e32 v165, v133, v133
	v_mul_f32_e32 v166, v135, v135
	v_fmac_f32_e32 v165, v132, v132
	v_fmac_f32_e32 v166, v134, v134
	v_add_f32_e32 v165, v165, v166
	v_add_f32_e32 v164, v164, v165
	v_mul_f32_e32 v165, v129, v129
	v_mul_f32_e32 v166, v131, v131
	v_fmac_f32_e32 v165, v128, v128
	v_fmac_f32_e32 v166, v130, v130
	v_add_f32_e32 v165, v165, v166
	v_add_f32_e32 v164, v164, v165
	v_mov_b32_e32 v165, v164
	s_nop 1
	v_permlane16_swap_b32_e32 v164, v165
	v_add_f32_e32 v164, v164, v165
	v_mov_b32_e32 v165, v164
	s_nop 1
	v_permlane32_swap_b32_e32 v164, v165
	v_add_f32_e32 v164, v164, v165
	v_fmamk_f32 v164, v164, 0x3c800000, v220
	v_rsq_f32_e32 v164, v164
	s_nop 0
	v_mul_f32_e32 v164, s73, v164

; __device__ __forceinline__ unsigned pk2(float lo, float hi) { const f32x2_cv v = {lo, hi}; const bf16x2_cv b = __builtin_convertvector(v, bf16x2_cv); return __builtin_bit_cast(unsigned, b); }
;     __device__ __forceinline__ void operator()(const pg8::f32x4 (&acc)[2][2][4][2], const pg8::Unit& u, int wr, int wc, int fr, int fq) const {
;     ...
;                 for (int bj = 0; bj < 2; ++bj) {
;                     pg8::f32x4 y0 = acc[ai][bj][m][0], y1 = acc[ai][bj][m][1];
;                     if (normed) {
;                         y0 = y0 * rinv * gg[bj][0]; y1 = y1 * rinv * gg[bj][1];
;                         if (lat) { const int p = bj == 0 ? (t >> 6) : (t & 63); const pg8::f32x4* rp = (const pg8::f32x4*)(rope + p * 16 + 4 * fq); const pg8::f32x4 c01 = rp[0], c23 = rp[1];
;                             const pg8::f32x4 z0 = {y0[0] * c01[0] - y0[1] * c01[1], y0[0] * c01[1] + y0[1] * c01[0], y0[2] * c01[2] - y0[3] * c01[3], y0[2] * c01[3] + y0[3] * c01[2]};
;                             const pg8::f32x4 z1 = {y1[0] * c23[0] - y1[1] * c23[1], y1[0] * c23[1] + y1[1] * c23[0], y1[2] * c23[2] - y1[3] * c23[3], y1[2] * c23[3] + y1[3] * c23[2]};
;                             y0 = z0; y1 = z1; }
;                     }
;                     v4u o; o.x = pk2(y0[0], y0[1]); o.y = pk2(y0[2], y0[3]); o.z = pk2(y1[0], y1[1]); o.w = pk2(y1[2], y1[3]);
;                     *(v4u*)(dp + 32 * bj) = o;
.LBB0_312:
	v_and_b32_e32 v245, 63, v162
	v_mul_lo_u32 v174, v163, s94
	v_mul_lo_u32 v175, v162, s95
	v_mad_u64_u32 v[162:163], s[4:5], v162, s94, 0
	v_add3_u32 v163, v163, v175, v174
	v_lshl_add_u64 v[162:163], v[162:163], 1, v[160:161]
	v_mul_u32_u24_e32 v244, s100, v245
	v_and_b32_e32 v245, 1, v245
	v_mad_u32_u24 v244, v245, s101, v244
	v_sub_u32_e32 v244, 0, v244
	v_ashrrev_i32_e32 v245, 31, v244
	v_lshl_add_u64 v[162:163], v[162:163], 0, v[244:245]
	v_cvt_pk_bf16_f32 v166, v166, v167
	v_cvt_pk_bf16_f32 v167, v172, v173
	v_cvt_pk_bf16_f32 v168, v168, v169
	v_cvt_pk_bf16_f32 v169, v170, v171
	global_store_dwordx4 v[162:163], v[166:169], off
	s_and_b64 vcc, exec, s[38:39]
	v_mov_b32_e32 v172, v134
	v_mov_b32_e32 v166, v132
	v_mov_b32_e32 v167, v133
	v_mov_b32_e32 v173, v135
	v_mov_b32_e32 v168, v128
	v_mov_b32_e32 v169, v129
	v_mov_b32_e32 v170, v130
	v_mov_b32_e32 v171, v131
	s_cbranch_vccnz .LBB0_316
	v_mov_b32_e32 v168, v164
	v_mov_b32_e32 v169, v164
	v_pk_mul_f32 v[166:167], v[134:135], v[168:169]
	v_pk_mul_f32 v[170:171], v[132:133], v[164:165]
	v_pk_mul_f32 v[168:169], v[130:131], v[168:169]
	v_pk_mul_f32 v[164:165], v[128:129], v[164:165]
	s_waitcnt vmcnt(0)
	v_pk_mul_f32 v[172:173], v[54:55], v[166:167]
	v_pk_mul_f32 v[166:167], v[52:53], v[170:171]
	v_pk_mul_f32 v[170:171], v[50:51], v[168:169]
	v_pk_mul_f32 v[168:169], v[48:49], v[164:165]
	s_and_saveexec_b64 s[4:5], s[40:41]
	s_cbranch_execz .LBB0_315
	v_lshlrev_b32_e32 v164, 7, v202
	v_and_b32_e32 v164, 0x780, v164
	v_mov_b32_e32 v165, v209
	v_lshl_add_u64 v[164:165], v[154:155], 0, v[164:165]
	global_load_dwordx4 v[174:177], v[164:165], off
	global_load_dwordx4 v[178:181], v[164:165], off offset:16
	s_waitcnt vmcnt(0) lgkmcnt(0)
	v_pk_mul_f32 v[182:183], v[166:167], v[174:175] op_sel:[1,1] op_sel_hi:[1,0]
	v_pk_mul_f32 v[164:165], v[166:167], v[174:175]
	v_pk_fma_f32 v[166:167], v[166:167], v[174:175], v[182:183] op_sel_hi:[0,1,1]
	v_mul_f32_e32 v166, v173, v177
	v_pk_fma_f32 v[174:175], v[172:173], v[176:177], v[166:167] op_sel_hi:[1,1,0] neg_lo:[0,0,1] neg_hi:[0,0,1]
	v_mul_f32_e32 v166, v173, v176
	v_pk_fma_f32 v[172:173], v[172:173], v[176:177], v[166:167] op_sel:[0,1,0] op_sel_hi:[1,0,0]
	v_pk_mul_f32 v[184:185], v[168:169], v[178:179] op_sel:[1,1] op_sel_hi:[1,0]
	v_mul_f32_e32 v166, v171, v181
	v_pk_mul_f32 v[176:177], v[168:169], v[178:179]
	v_pk_fma_f32 v[168:169], v[168:169], v[178:179], v[184:185] op_sel_hi:[0,1,1]
	v_pk_fma_f32 v[178:179], v[170:171], v[180:181], v[166:167] op_sel_hi:[1,1,0] neg_lo:[0,0,1] neg_hi:[0,0,1]
	v_mul_f32_e32 v166, v171, v180
	v_pk_fma_f32 v[170:171], v[170:171], v[180:181], v[166:167] op_sel:[0,1,0] op_sel_hi:[1,0,0]
	v_sub_f32_e32 v166, v164, v182
	v_sub_f32_e32 v168, v176, v184
	v_mov_b32_e32 v171, v170
	v_mov_b32_e32 v170, v178
	v_mov_b32_e32 v173, v172
	v_mov_b32_e32 v172, v174

; __device__ __forceinline__ unsigned pk2(float lo, float hi) { const f32x2_cv v = {lo, hi}; const bf16x2_cv b = __builtin_convertvector(v, bf16x2_cv); return __builtin_bit_cast(unsigned, b); }
;     __device__ __forceinline__ void operator()(const pg8::f32x4 (&acc)[2][2][4][2], const pg8::Unit& u, int wr, int wc, int fr, int fq) const {
;     ...
;                 for (int bj = 0; bj < 2; ++bj) {
;                     pg8::f32x4 y0 = acc[ai][bj][m][0], y1 = acc[ai][bj][m][1];
;                     if (normed) {
;                         y0 = y0 * rinv * gg[bj][0]; y1 = y1 * rinv * gg[bj][1];
;                         if (lat) { const int p = bj == 0 ? (t >> 6) : (t & 63); const pg8::f32x4* rp = (const pg8::f32x4*)(rope + p * 16 + 4 * fq); const pg8::f32x4 c01 = rp[0], c23 = rp[1];
;                             const pg8::f32x4 z0 = {y0[0] * c01[0] - y0[1] * c01[1], y0[0] * c01[1] + y0[1] * c01[0], y0[2] * c01[2] - y0[3] * c01[3], y0[2] * c01[3] + y0[3] * c01[2]};
;                             const pg8::f32x4 z1 = {y1[0] * c23[0] - y1[1] * c23[1], y1[0] * c23[1] + y1[1] * c23[0], y1[2] * c23[2] - y1[3] * c23[3], y1[2] * c23[3] + y1[3] * c23[2]};
;                             y0 = z0; y1 = z1; }
;                     }
;                     v4u o; o.x = pk2(y0[0], y0[1]); o.y = pk2(y0[2], y0[3]); o.z = pk2(y1[0], y1[1]); o.w = pk2(y1[2], y1[3]);
;                     *(v4u*)(dp + 32 * bj) = o;
.LBB0_330:
	v_and_b32_e32 v245, 63, v128
	v_mul_lo_u32 v142, v129, s94
	v_mul_lo_u32 v143, v128, s95
	v_mad_u64_u32 v[128:129], s[4:5], v128, s94, 0
	v_add3_u32 v129, v129, v143, v142
	v_lshl_add_u64 v[128:129], v[128:129], 1, v[160:161]
	v_mul_u32_u24_e32 v244, s100, v245
	v_and_b32_e32 v245, 1, v245
	v_mad_u32_u24 v244, v245, s101, v244
	v_sub_u32_e32 v244, 0, v244
	v_ashrrev_i32_e32 v245, 31, v244
	v_lshl_add_u64 v[128:129], v[128:129], 0, v[244:245]
	v_cvt_pk_bf16_f32 v132, v132, v133
	v_cvt_pk_bf16_f32 v133, v138, v139
	v_cvt_pk_bf16_f32 v134, v134, v135
	v_cvt_pk_bf16_f32 v135, v136, v137
	global_store_dwordx4 v[128:129], v[132:135], off
	s_and_b64 vcc, exec, s[38:39]
	v_mov_b32_e32 v138, v118
	v_mov_b32_e32 v132, v116
	v_mov_b32_e32 v133, v117
	v_mov_b32_e32 v139, v119
	v_mov_b32_e32 v134, v112
	v_mov_b32_e32 v135, v113
	v_mov_b32_e32 v136, v114
	v_mov_b32_e32 v137, v115
	s_cbranch_vccnz .LBB0_334
	v_mov_b32_e32 v134, v130
	v_mov_b32_e32 v135, v130
	v_pk_mul_f32 v[132:133], v[118:119], v[134:135]
	v_pk_mul_f32 v[136:137], v[116:117], v[130:131]
	v_pk_mul_f32 v[134:135], v[114:115], v[134:135]
	v_pk_mul_f32 v[130:131], v[112:113], v[130:131]
	s_waitcnt vmcnt(0)
	v_pk_mul_f32 v[138:139], v[54:55], v[132:133]
	v_pk_mul_f32 v[132:133], v[52:53], v[136:137]
	v_pk_mul_f32 v[136:137], v[50:51], v[134:135]
	v_pk_mul_f32 v[134:135], v[48:49], v[130:131]
	s_and_saveexec_b64 s[4:5], s[44:45]
	s_cbranch_execz .LBB0_333
	v_lshlrev_b32_e32 v130, 7, v141
	v_and_b32_e32 v130, 0xf80, v130
	v_mov_b32_e32 v131, v209
	v_lshl_add_u64 v[130:131], v[154:155], 0, v[130:131]
	global_load_dwordx4 v[202:205], v[130:131], off
	global_load_dwordx4 v[210:213], v[130:131], off offset:16
	s_waitcnt vmcnt(0) lgkmcnt(0)
	v_pk_mul_f32 v[142:143], v[132:133], v[202:203] op_sel:[1,1] op_sel_hi:[1,0]
	v_pk_mul_f32 v[130:131], v[132:133], v[202:203]
	v_pk_fma_f32 v[132:133], v[132:133], v[202:203], v[142:143] op_sel_hi:[0,1,1]
	v_mul_f32_e32 v132, v139, v205
	v_pk_fma_f32 v[202:203], v[138:139], v[204:205], v[132:133] op_sel_hi:[1,1,0] neg_lo:[0,0,1] neg_hi:[0,0,1]
	v_mul_f32_e32 v132, v139, v204
	v_pk_fma_f32 v[138:139], v[138:139], v[204:205], v[132:133] op_sel:[0,1,0] op_sel_hi:[1,0,0]
	v_pk_mul_f32 v[206:207], v[134:135], v[210:211] op_sel:[1,1] op_sel_hi:[1,0]
	v_mul_f32_e32 v132, v137, v213
	v_pk_mul_f32 v[204:205], v[134:135], v[210:211]
	v_pk_fma_f32 v[134:135], v[134:135], v[210:211], v[206:207] op_sel_hi:[0,1,1]
	v_pk_fma_f32 v[210:211], v[136:137], v[212:213], v[132:133] op_sel_hi:[1,1,0] neg_lo:[0,0,1] neg_hi:[0,0,1]
	v_mul_f32_e32 v132, v137, v212
	v_pk_fma_f32 v[136:137], v[136:137], v[212:213], v[132:133] op_sel:[0,1,0] op_sel_hi:[1,0,0]
	v_sub_f32_e32 v132, v130, v142
	v_sub_f32_e32 v134, v204, v206
	v_mov_b32_e32 v137, v136
	v_mov_b32_e32 v136, v210
	v_mov_b32_e32 v139, v138
	v_mov_b32_e32 v138, v202

; __device__ __forceinline__ unsigned pk2(float lo, float hi) { const f32x2_cv v = {lo, hi}; const bf16x2_cv b = __builtin_convertvector(v, bf16x2_cv); return __builtin_bit_cast(unsigned, b); }
;     __device__ __forceinline__ void operator()(const pg8::f32x4 (&acc)[2][2][4][2], const pg8::Unit& u, int wr, int wc, int fr, int fq) const {
;     ...
;                 for (int bj = 0; bj < 2; ++bj) {
;                     pg8::f32x4 y0 = acc[ai][bj][m][0], y1 = acc[ai][bj][m][1];
;                     if (normed) {
;                         y0 = y0 * rinv * gg[bj][0]; y1 = y1 * rinv * gg[bj][1];
;                         if (lat) { const int p = bj == 0 ? (t >> 6) : (t & 63); const pg8::f32x4* rp = (const pg8::f32x4*)(rope + p * 16 + 4 * fq); const pg8::f32x4 c01 = rp[0], c23 = rp[1];
;                             const pg8::f32x4 z0 = {y0[0] * c01[0] - y0[1] * c01[1], y0[0] * c01[1] + y0[1] * c01[0], y0[2] * c01[2] - y0[3] * c01[3], y0[2] * c01[3] + y0[3] * c01[2]};
;                             const pg8::f32x4 z1 = {y1[0] * c23[0] - y1[1] * c23[1], y1[0] * c23[1] + y1[1] * c23[0], y1[2] * c23[2] - y1[3] * c23[3], y1[2] * c23[3] + y1[3] * c23[2]};
;                             y0 = z0; y1 = z1; }
;                     }
;                     v4u o; o.x = pk2(y0[0], y0[1]); o.y = pk2(y0[2], y0[3]); o.z = pk2(y1[0], y1[1]); o.w = pk2(y1[2], y1[3]);
;                     *(v4u*)(dp + 32 * bj) = o;
.LBB0_383:
	v_and_b32_e32 v245, 63, v112
	v_mul_lo_u32 v126, v113, s94
	v_mul_lo_u32 v127, v112, s95
	v_mad_u64_u32 v[112:113], s[4:5], v112, s94, 0
	v_add3_u32 v113, v113, v127, v126
	v_lshl_add_u64 v[112:113], v[112:113], 1, v[160:161]
	v_mul_u32_u24_e32 v244, s100, v245
	v_and_b32_e32 v245, 1, v245
	v_mad_u32_u24 v244, v245, s101, v244
	v_sub_u32_e32 v244, 0, v244
	v_ashrrev_i32_e32 v245, 31, v244
	v_lshl_add_u64 v[112:113], v[112:113], 0, v[244:245]
	v_cvt_pk_bf16_f32 v116, v116, v117
	v_cvt_pk_bf16_f32 v117, v122, v123
	v_cvt_pk_bf16_f32 v118, v118, v119
	v_cvt_pk_bf16_f32 v119, v120, v121
	global_store_dwordx4 v[112:113], v[116:119], off
	s_and_b64 vcc, exec, s[38:39]
	v_mov_b32_e32 v122, v102
	v_mov_b32_e32 v116, v100
	v_mov_b32_e32 v117, v101
	v_mov_b32_e32 v123, v103
	v_mov_b32_e32 v118, v96
	v_mov_b32_e32 v119, v97
	v_mov_b32_e32 v120, v98
	v_mov_b32_e32 v121, v99
	s_cbranch_vccnz .LBB0_387
	v_mov_b32_e32 v118, v114
	v_mov_b32_e32 v119, v114
	v_pk_mul_f32 v[116:117], v[102:103], v[118:119]
	v_pk_mul_f32 v[120:121], v[100:101], v[114:115]
	v_pk_mul_f32 v[118:119], v[98:99], v[118:119]
	v_pk_mul_f32 v[114:115], v[96:97], v[114:115]
	s_waitcnt vmcnt(0)
	v_pk_mul_f32 v[122:123], v[54:55], v[116:117]
	v_pk_mul_f32 v[116:117], v[52:53], v[120:121]
	v_pk_mul_f32 v[120:121], v[50:51], v[118:119]
	v_pk_mul_f32 v[118:119], v[48:49], v[114:115]
	s_and_saveexec_b64 s[4:5], s[44:45]
	s_cbranch_execz .LBB0_386
	v_lshlrev_b32_e32 v114, 7, v125
	v_and_b32_e32 v114, 0x1780, v114
	v_mov_b32_e32 v115, v209
	v_lshl_add_u64 v[114:115], v[154:155], 0, v[114:115]
	global_load_dwordx4 v[126:129], v[114:115], off
	global_load_dwordx4 v[130:133], v[114:115], off offset:16
	s_waitcnt vmcnt(0) lgkmcnt(0)
	v_pk_mul_f32 v[134:135], v[116:117], v[126:127] op_sel:[1,1] op_sel_hi:[1,0]
	v_pk_mul_f32 v[114:115], v[116:117], v[126:127]
	v_pk_fma_f32 v[116:117], v[116:117], v[126:127], v[134:135] op_sel_hi:[0,1,1]
	v_mul_f32_e32 v116, v123, v129
	v_pk_fma_f32 v[126:127], v[122:123], v[128:129], v[116:117] op_sel_hi:[1,1,0] neg_lo:[0,0,1] neg_hi:[0,0,1]
	v_mul_f32_e32 v116, v123, v128
	v_pk_fma_f32 v[122:123], v[122:123], v[128:129], v[116:117] op_sel:[0,1,0] op_sel_hi:[1,0,0]
	v_pk_mul_f32 v[136:137], v[118:119], v[130:131] op_sel:[1,1] op_sel_hi:[1,0]
	v_mul_f32_e32 v116, v121, v133
	v_pk_mul_f32 v[128:129], v[118:119], v[130:131]
	v_pk_fma_f32 v[118:119], v[118:119], v[130:131], v[136:137] op_sel_hi:[0,1,1]
	v_pk_fma_f32 v[130:131], v[120:121], v[132:133], v[116:117] op_sel_hi:[1,1,0] neg_lo:[0,0,1] neg_hi:[0,0,1]
	v_mul_f32_e32 v116, v121, v132
	v_pk_fma_f32 v[120:121], v[120:121], v[132:133], v[116:117] op_sel:[0,1,0] op_sel_hi:[1,0,0]
	v_sub_f32_e32 v116, v114, v134
	v_sub_f32_e32 v118, v128, v136
	v_mov_b32_e32 v121, v120
	v_mov_b32_e32 v120, v130
	v_mov_b32_e32 v123, v122
	v_mov_b32_e32 v122, v126

; __device__ __forceinline__ unsigned pk2(float lo, float hi) { const f32x2_cv v = {lo, hi}; const bf16x2_cv b = __builtin_convertvector(v, bf16x2_cv); return __builtin_bit_cast(unsigned, b); }
;     __device__ __forceinline__ void operator()(const pg8::f32x4 (&acc)[2][2][4][2], const pg8::Unit& u, int wr, int wc, int fr, int fq) const {
;     ...
;                 for (int bj = 0; bj < 2; ++bj) {
;                     pg8::f32x4 y0 = acc[ai][bj][m][0], y1 = acc[ai][bj][m][1];
;                     if (normed) {
;                         y0 = y0 * rinv * gg[bj][0]; y1 = y1 * rinv * gg[bj][1];
;                         if (lat) { const int p = bj == 0 ? (t >> 6) : (t & 63); const pg8::f32x4* rp = (const pg8::f32x4*)(rope + p * 16 + 4 * fq); const pg8::f32x4 c01 = rp[0], c23 = rp[1];
;                             const pg8::f32x4 z0 = {y0[0] * c01[0] - y0[1] * c01[1], y0[0] * c01[1] + y0[1] * c01[0], y0[2] * c01[2] - y0[3] * c01[3], y0[2] * c01[3] + y0[3] * c01[2]};
;                             const pg8::f32x4 z1 = {y1[0] * c23[0] - y1[1] * c23[1], y1[0] * c23[1] + y1[1] * c23[0], y1[2] * c23[2] - y1[3] * c23[3], y1[2] * c23[3] + y1[3] * c23[2]};
;                             y0 = z0; y1 = z1; }
;                     }
;                     v4u o; o.x = pk2(y0[0], y0[1]); o.y = pk2(y0[2], y0[3]); o.z = pk2(y1[0], y1[1]); o.w = pk2(y1[2], y1[3]);
;                     *(v4u*)(dp + 32 * bj) = o;
.LBB0_395:
	v_and_b32_e32 v245, 63, v96
	v_mul_lo_u32 v110, v97, s94
	v_mul_lo_u32 v111, v96, s95
	v_mad_u64_u32 v[96:97], s[4:5], v96, s94, 0
	v_add3_u32 v97, v97, v111, v110
	v_lshl_add_u64 v[96:97], v[96:97], 1, v[160:161]
	v_mul_u32_u24_e32 v244, s100, v245
	v_and_b32_e32 v245, 1, v245
	v_mad_u32_u24 v244, v245, s101, v244
	v_sub_u32_e32 v244, 0, v244
	v_ashrrev_i32_e32 v245, 31, v244
	v_lshl_add_u64 v[96:97], v[96:97], 0, v[244:245]
	v_cvt_pk_bf16_f32 v100, v100, v101
	v_cvt_pk_bf16_f32 v101, v106, v107
	v_cvt_pk_bf16_f32 v102, v102, v103
	v_cvt_pk_bf16_f32 v103, v104, v105
	global_store_dwordx4 v[96:97], v[100:103], off
	s_and_b64 vcc, exec, s[38:39]
	v_mov_b32_e32 v106, v86
	v_mov_b32_e32 v100, v84
	v_mov_b32_e32 v101, v85
	v_mov_b32_e32 v107, v87
	v_mov_b32_e32 v102, v80
	v_mov_b32_e32 v103, v81
	v_mov_b32_e32 v104, v82
	v_mov_b32_e32 v105, v83
	s_cbranch_vccnz .LBB0_399
	v_mov_b32_e32 v102, v98
	v_mov_b32_e32 v103, v98
	v_pk_mul_f32 v[100:101], v[86:87], v[102:103]
	v_pk_mul_f32 v[104:105], v[84:85], v[98:99]
	v_pk_mul_f32 v[102:103], v[82:83], v[102:103]
	v_pk_mul_f32 v[98:99], v[80:81], v[98:99]
	s_waitcnt vmcnt(0)
	v_pk_mul_f32 v[106:107], v[54:55], v[100:101]
	v_pk_mul_f32 v[100:101], v[52:53], v[104:105]
	v_pk_mul_f32 v[104:105], v[50:51], v[102:103]
	v_pk_mul_f32 v[102:103], v[48:49], v[98:99]
	s_and_saveexec_b64 s[4:5], s[44:45]
	s_cbranch_execz .LBB0_398
	v_lshlrev_b32_e32 v98, 7, v109
	v_and_b32_e32 v98, 0x1f80, v98
	v_mov_b32_e32 v99, v209
	v_lshl_add_u64 v[98:99], v[154:155], 0, v[98:99]
	global_load_dwordx4 v[110:113], v[98:99], off
	global_load_dwordx4 v[114:117], v[98:99], off offset:16
	s_waitcnt vmcnt(0) lgkmcnt(0)
	v_pk_mul_f32 v[118:119], v[100:101], v[110:111] op_sel:[1,1] op_sel_hi:[1,0]
	v_pk_mul_f32 v[98:99], v[100:101], v[110:111]
	v_pk_fma_f32 v[100:101], v[100:101], v[110:111], v[118:119] op_sel_hi:[0,1,1]
	v_mul_f32_e32 v100, v107, v113
	v_pk_fma_f32 v[110:111], v[106:107], v[112:113], v[100:101] op_sel_hi:[1,1,0] neg_lo:[0,0,1] neg_hi:[0,0,1]
	v_mul_f32_e32 v100, v107, v112
	v_pk_fma_f32 v[106:107], v[106:107], v[112:113], v[100:101] op_sel:[0,1,0] op_sel_hi:[1,0,0]
	v_pk_mul_f32 v[120:121], v[102:103], v[114:115] op_sel:[1,1] op_sel_hi:[1,0]
	v_mul_f32_e32 v100, v105, v117
	v_pk_mul_f32 v[112:113], v[102:103], v[114:115]
	v_pk_fma_f32 v[102:103], v[102:103], v[114:115], v[120:121] op_sel_hi:[0,1,1]
	v_pk_fma_f32 v[114:115], v[104:105], v[116:117], v[100:101] op_sel_hi:[1,1,0] neg_lo:[0,0,1] neg_hi:[0,0,1]
	v_mul_f32_e32 v100, v105, v116
	v_pk_fma_f32 v[104:105], v[104:105], v[116:117], v[100:101] op_sel:[0,1,0] op_sel_hi:[1,0,0]
	v_sub_f32_e32 v100, v98, v118
	v_sub_f32_e32 v102, v112, v120
	v_mov_b32_e32 v105, v104
	v_mov_b32_e32 v104, v114
	v_mov_b32_e32 v107, v106
	v_mov_b32_e32 v106, v110

; __device__ __forceinline__ unsigned pk2(float lo, float hi) { const f32x2_cv v = {lo, hi}; const bf16x2_cv b = __builtin_convertvector(v, bf16x2_cv); return __builtin_bit_cast(unsigned, b); }
;     __device__ __forceinline__ void operator()(const pg8::f32x4 (&acc)[2][2][4][2], const pg8::Unit& u, int wr, int wc, int fr, int fq) const {
;     ...
;                 for (int bj = 0; bj < 2; ++bj) {
;                     pg8::f32x4 y0 = acc[ai][bj][m][0], y1 = acc[ai][bj][m][1];
;                     if (normed) {
;                         y0 = y0 * rinv * gg[bj][0]; y1 = y1 * rinv * gg[bj][1];
;                         if (lat) { const int p = bj == 0 ? (t >> 6) : (t & 63); const pg8::f32x4* rp = (const pg8::f32x4*)(rope + p * 16 + 4 * fq); const pg8::f32x4 c01 = rp[0], c23 = rp[1];
;                             const pg8::f32x4 z0 = {y0[0] * c01[0] - y0[1] * c01[1], y0[0] * c01[1] + y0[1] * c01[0], y0[2] * c01[2] - y0[3] * c01[3], y0[2] * c01[3] + y0[3] * c01[2]};
;                             const pg8::f32x4 z1 = {y1[0] * c23[0] - y1[1] * c23[1], y1[0] * c23[1] + y1[1] * c23[0], y1[2] * c23[2] - y1[3] * c23[3], y1[2] * c23[3] + y1[3] * c23[2]};
;                             y0 = z0; y1 = z1; }
;                     }
;                     v4u o; o.x = pk2(y0[0], y0[1]); o.y = pk2(y0[2], y0[3]); o.z = pk2(y1[0], y1[1]); o.w = pk2(y1[2], y1[3]);
;                     *(v4u*)(dp + 32 * bj) = o;
.LBB0_407:
	v_and_b32_e32 v245, 63, v80
	v_mul_lo_u32 v94, v81, s94
	v_mul_lo_u32 v95, v80, s95
	v_mad_u64_u32 v[80:81], s[4:5], v80, s94, 0
	v_add3_u32 v81, v81, v95, v94
	v_lshl_add_u64 v[80:81], v[80:81], 1, v[160:161]
	v_mul_u32_u24_e32 v244, s100, v245
	v_and_b32_e32 v245, 1, v245
	v_mad_u32_u24 v244, v245, s101, v244
	v_sub_u32_e32 v244, 0, v244
	v_ashrrev_i32_e32 v245, 31, v244
	v_lshl_add_u64 v[80:81], v[80:81], 0, v[244:245]
	v_cvt_pk_bf16_f32 v84, v84, v85
	v_cvt_pk_bf16_f32 v85, v90, v91
	v_cvt_pk_bf16_f32 v86, v86, v87
	v_cvt_pk_bf16_f32 v87, v88, v89
	global_store_dwordx4 v[80:81], v[84:87], off
	s_and_b64 vcc, exec, s[38:39]
	v_mov_b32_e32 v90, v70
	v_mov_b32_e32 v84, v68
	v_mov_b32_e32 v85, v69
	v_mov_b32_e32 v91, v71
	v_mov_b32_e32 v86, v64
	v_mov_b32_e32 v87, v65
	v_mov_b32_e32 v88, v66
	v_mov_b32_e32 v89, v67
	s_cbranch_vccnz .LBB0_411
	v_mov_b32_e32 v86, v82
	v_mov_b32_e32 v87, v82
	v_pk_mul_f32 v[84:85], v[70:71], v[86:87]
	v_pk_mul_f32 v[88:89], v[68:69], v[82:83]
	v_pk_mul_f32 v[86:87], v[66:67], v[86:87]
	v_pk_mul_f32 v[82:83], v[64:65], v[82:83]
	s_waitcnt vmcnt(0)
	v_pk_mul_f32 v[90:91], v[54:55], v[84:85]
	v_pk_mul_f32 v[84:85], v[52:53], v[88:89]
	v_pk_mul_f32 v[88:89], v[50:51], v[86:87]
	v_pk_mul_f32 v[86:87], v[48:49], v[82:83]
	s_and_saveexec_b64 s[4:5], s[44:45]
	s_cbranch_execz .LBB0_410
	v_lshlrev_b32_e32 v82, 7, v93
	v_and_b32_e32 v82, 0x780, v82
	v_mov_b32_e32 v83, v209
	v_lshl_add_u64 v[82:83], v[154:155], 0, v[82:83]
	global_load_dwordx4 v[94:97], v[82:83], off
	global_load_dwordx4 v[98:101], v[82:83], off offset:16
	s_waitcnt vmcnt(0) lgkmcnt(0)
	v_pk_mul_f32 v[102:103], v[84:85], v[94:95] op_sel:[1,1] op_sel_hi:[1,0]
	v_pk_mul_f32 v[82:83], v[84:85], v[94:95]
	v_pk_fma_f32 v[84:85], v[84:85], v[94:95], v[102:103] op_sel_hi:[0,1,1]
	v_mul_f32_e32 v84, v91, v97
	v_pk_fma_f32 v[94:95], v[90:91], v[96:97], v[84:85] op_sel_hi:[1,1,0] neg_lo:[0,0,1] neg_hi:[0,0,1]
	v_mul_f32_e32 v84, v91, v96
	v_pk_fma_f32 v[90:91], v[90:91], v[96:97], v[84:85] op_sel:[0,1,0] op_sel_hi:[1,0,0]
	v_pk_mul_f32 v[104:105], v[86:87], v[98:99] op_sel:[1,1] op_sel_hi:[1,0]
	v_mul_f32_e32 v84, v89, v101
	v_pk_mul_f32 v[96:97], v[86:87], v[98:99]
	v_pk_fma_f32 v[86:87], v[86:87], v[98:99], v[104:105] op_sel_hi:[0,1,1]
	v_pk_fma_f32 v[98:99], v[88:89], v[100:101], v[84:85] op_sel_hi:[1,1,0] neg_lo:[0,0,1] neg_hi:[0,0,1]
	v_mul_f32_e32 v84, v89, v100
	v_pk_fma_f32 v[88:89], v[88:89], v[100:101], v[84:85] op_sel:[0,1,0] op_sel_hi:[1,0,0]
	v_sub_f32_e32 v84, v82, v102
	v_sub_f32_e32 v86, v96, v104
	v_mov_b32_e32 v89, v88
	v_mov_b32_e32 v88, v98
	v_mov_b32_e32 v91, v90
	v_mov_b32_e32 v90, v94

; __device__ __forceinline__ unsigned pk2(float lo, float hi) { const f32x2_cv v = {lo, hi}; const bf16x2_cv b = __builtin_convertvector(v, bf16x2_cv); return __builtin_bit_cast(unsigned, b); }
;     __device__ __forceinline__ void operator()(const pg8::f32x4 (&acc)[2][2][4][2], const pg8::Unit& u, int wr, int wc, int fr, int fq) const {
;     ...
;                 for (int bj = 0; bj < 2; ++bj) {
;                     pg8::f32x4 y0 = acc[ai][bj][m][0], y1 = acc[ai][bj][m][1];
;                     if (normed) {
;                         y0 = y0 * rinv * gg[bj][0]; y1 = y1 * rinv * gg[bj][1];
;                         if (lat) { const int p = bj == 0 ? (t >> 6) : (t & 63); const pg8::f32x4* rp = (const pg8::f32x4*)(rope + p * 16 + 4 * fq); const pg8::f32x4 c01 = rp[0], c23 = rp[1];
;                             const pg8::f32x4 z0 = {y0[0] * c01[0] - y0[1] * c01[1], y0[0] * c01[1] + y0[1] * c01[0], y0[2] * c01[2] - y0[3] * c01[3], y0[2] * c01[3] + y0[3] * c01[2]};
;                             const pg8::f32x4 z1 = {y1[0] * c23[0] - y1[1] * c23[1], y1[0] * c23[1] + y1[1] * c23[0], y1[2] * c23[2] - y1[3] * c23[3], y1[2] * c23[3] + y1[3] * c23[2]};
;                             y0 = z0; y1 = z1; }
;                     }
;                     v4u o; o.x = pk2(y0[0], y0[1]); o.y = pk2(y0[2], y0[3]); o.z = pk2(y1[0], y1[1]); o.w = pk2(y1[2], y1[3]);
;                     *(v4u*)(dp + 32 * bj) = o;
.LBB0_419:
	v_and_b32_e32 v245, 63, v64
	v_mul_lo_u32 v78, v65, s94
	v_mul_lo_u32 v79, v64, s95
	v_mad_u64_u32 v[64:65], s[4:5], v64, s94, 0
	v_add3_u32 v65, v65, v79, v78
	v_lshl_add_u64 v[64:65], v[64:65], 1, v[160:161]
	v_mul_u32_u24_e32 v244, s100, v245
	v_and_b32_e32 v245, 1, v245
	v_mad_u32_u24 v244, v245, s101, v244
	v_sub_u32_e32 v244, 0, v244
	v_ashrrev_i32_e32 v245, 31, v244
	v_lshl_add_u64 v[64:65], v[64:65], 0, v[244:245]
	v_cvt_pk_bf16_f32 v68, v68, v69
	v_cvt_pk_bf16_f32 v69, v74, v75
	v_cvt_pk_bf16_f32 v70, v70, v71
	v_cvt_pk_bf16_f32 v71, v72, v73
	global_store_dwordx4 v[64:65], v[68:71], off
	s_and_b64 vcc, exec, s[38:39]
	v_mov_b32_e32 v74, v38
	v_mov_b32_e32 v68, v36
	v_mov_b32_e32 v69, v37
	v_mov_b32_e32 v75, v39
	v_mov_b32_e32 v70, v32
	v_mov_b32_e32 v71, v33
	v_mov_b32_e32 v72, v34
	v_mov_b32_e32 v73, v35
	s_cbranch_vccnz .LBB0_423
	v_mov_b32_e32 v70, v66
	v_mov_b32_e32 v71, v66
	v_pk_mul_f32 v[68:69], v[38:39], v[70:71]
	v_pk_mul_f32 v[72:73], v[36:37], v[66:67]
	v_pk_mul_f32 v[70:71], v[34:35], v[70:71]
	v_pk_mul_f32 v[66:67], v[32:33], v[66:67]
	s_waitcnt vmcnt(0)
	v_pk_mul_f32 v[74:75], v[54:55], v[68:69]
	v_pk_mul_f32 v[68:69], v[52:53], v[72:73]
	v_pk_mul_f32 v[72:73], v[50:51], v[70:71]
	v_pk_mul_f32 v[70:71], v[48:49], v[66:67]
	s_and_saveexec_b64 s[4:5], s[44:45]
	s_cbranch_execz .LBB0_422
	v_lshlrev_b32_e32 v66, 7, v77
	v_and_b32_e32 v66, 0xf80, v66
	v_mov_b32_e32 v67, v209
	v_lshl_add_u64 v[66:67], v[154:155], 0, v[66:67]
	global_load_dwordx4 v[78:81], v[66:67], off
	global_load_dwordx4 v[82:85], v[66:67], off offset:16
	s_waitcnt vmcnt(0) lgkmcnt(0)
	v_pk_mul_f32 v[86:87], v[68:69], v[78:79] op_sel:[1,1] op_sel_hi:[1,0]
	v_pk_mul_f32 v[66:67], v[68:69], v[78:79]
	v_pk_fma_f32 v[68:69], v[68:69], v[78:79], v[86:87] op_sel_hi:[0,1,1]
	v_mul_f32_e32 v68, v75, v81
	v_pk_fma_f32 v[78:79], v[74:75], v[80:81], v[68:69] op_sel_hi:[1,1,0] neg_lo:[0,0,1] neg_hi:[0,0,1]
	v_mul_f32_e32 v68, v75, v80
	v_pk_fma_f32 v[74:75], v[74:75], v[80:81], v[68:69] op_sel:[0,1,0] op_sel_hi:[1,0,0]
	v_pk_mul_f32 v[88:89], v[70:71], v[82:83] op_sel:[1,1] op_sel_hi:[1,0]
	v_mul_f32_e32 v68, v73, v85
	v_pk_mul_f32 v[80:81], v[70:71], v[82:83]
	v_pk_fma_f32 v[70:71], v[70:71], v[82:83], v[88:89] op_sel_hi:[0,1,1]
	v_pk_fma_f32 v[82:83], v[72:73], v[84:85], v[68:69] op_sel_hi:[1,1,0] neg_lo:[0,0,1] neg_hi:[0,0,1]
	v_mul_f32_e32 v68, v73, v84
	v_pk_fma_f32 v[72:73], v[72:73], v[84:85], v[68:69] op_sel:[0,1,0] op_sel_hi:[1,0,0]
	v_sub_f32_e32 v68, v66, v86
	v_sub_f32_e32 v70, v80, v88
	v_mov_b32_e32 v73, v72
	v_mov_b32_e32 v72, v82
	v_mov_b32_e32 v75, v74
	v_mov_b32_e32 v74, v78

; __device__ __forceinline__ unsigned pk2(float lo, float hi) { const f32x2_cv v = {lo, hi}; const bf16x2_cv b = __builtin_convertvector(v, bf16x2_cv); return __builtin_bit_cast(unsigned, b); }
;     __device__ __forceinline__ void operator()(const pg8::f32x4 (&acc)[2][2][4][2], const pg8::Unit& u, int wr, int wc, int fr, int fq) const {
;     ...
;                 for (int bj = 0; bj < 2; ++bj) {
;                     pg8::f32x4 y0 = acc[ai][bj][m][0], y1 = acc[ai][bj][m][1];
;                     if (normed) {
;                         y0 = y0 * rinv * gg[bj][0]; y1 = y1 * rinv * gg[bj][1];
;                         if (lat) { const int p = bj == 0 ? (t >> 6) : (t & 63); const pg8::f32x4* rp = (const pg8::f32x4*)(rope + p * 16 + 4 * fq); const pg8::f32x4 c01 = rp[0], c23 = rp[1];
;                             const pg8::f32x4 z0 = {y0[0] * c01[0] - y0[1] * c01[1], y0[0] * c01[1] + y0[1] * c01[0], y0[2] * c01[2] - y0[3] * c01[3], y0[2] * c01[3] + y0[3] * c01[2]};
;                             const pg8::f32x4 z1 = {y1[0] * c23[0] - y1[1] * c23[1], y1[0] * c23[1] + y1[1] * c23[0], y1[2] * c23[2] - y1[3] * c23[3], y1[2] * c23[3] + y1[3] * c23[2]};
;                             y0 = z0; y1 = z1; }
;                     }
;                     v4u o; o.x = pk2(y0[0], y0[1]); o.y = pk2(y0[2], y0[3]); o.z = pk2(y1[0], y1[1]); o.w = pk2(y1[2], y1[3]);
;                     *(v4u*)(dp + 32 * bj) = o;
.LBB0_431:
	v_and_b32_e32 v245, 63, v32
	v_mul_lo_u32 v46, v33, s94
	v_mul_lo_u32 v47, v32, s95
	v_mad_u64_u32 v[32:33], s[4:5], v32, s94, 0
	v_add3_u32 v33, v33, v47, v46
	v_lshl_add_u64 v[32:33], v[32:33], 1, v[160:161]
	v_mul_u32_u24_e32 v244, s100, v245
	v_and_b32_e32 v245, 1, v245
	v_mad_u32_u24 v244, v245, s101, v244
	v_sub_u32_e32 v244, 0, v244
	v_ashrrev_i32_e32 v245, 31, v244
	v_lshl_add_u64 v[32:33], v[32:33], 0, v[244:245]
	v_cvt_pk_bf16_f32 v36, v36, v37
	v_cvt_pk_bf16_f32 v37, v42, v43
	v_cvt_pk_bf16_f32 v38, v38, v39
	v_cvt_pk_bf16_f32 v39, v40, v41
	global_store_dwordx4 v[32:33], v[36:39], off
	s_and_b64 vcc, exec, s[38:39]
	v_mov_b32_e32 v42, v22
	v_mov_b32_e32 v36, v20
	v_mov_b32_e32 v37, v21
	v_mov_b32_e32 v43, v23
	v_mov_b32_e32 v38, v16
	v_mov_b32_e32 v39, v17
	v_mov_b32_e32 v40, v18
	v_mov_b32_e32 v41, v19
	s_cbranch_vccnz .LBB0_435
	v_mov_b32_e32 v38, v34
	v_mov_b32_e32 v39, v34
	v_pk_mul_f32 v[36:37], v[22:23], v[38:39]
	v_pk_mul_f32 v[40:41], v[20:21], v[34:35]
	v_pk_mul_f32 v[38:39], v[18:19], v[38:39]
	v_pk_mul_f32 v[34:35], v[16:17], v[34:35]
	s_waitcnt vmcnt(0)
	v_pk_mul_f32 v[42:43], v[54:55], v[36:37]
	v_pk_mul_f32 v[36:37], v[52:53], v[40:41]
	v_pk_mul_f32 v[40:41], v[50:51], v[38:39]
	v_pk_mul_f32 v[38:39], v[48:49], v[34:35]
	s_and_saveexec_b64 s[4:5], s[44:45]
	s_cbranch_execz .LBB0_434
	v_lshlrev_b32_e32 v34, 7, v45
	v_and_b32_e32 v34, 0x1780, v34
	v_mov_b32_e32 v35, v209
	v_lshl_add_u64 v[34:35], v[154:155], 0, v[34:35]
	global_load_dwordx4 v[64:67], v[34:35], off
	global_load_dwordx4 v[68:71], v[34:35], off offset:16
	s_waitcnt vmcnt(0) lgkmcnt(0)
	v_pk_mul_f32 v[46:47], v[36:37], v[64:65] op_sel:[1,1] op_sel_hi:[1,0]
	v_pk_mul_f32 v[34:35], v[36:37], v[64:65]
	v_pk_fma_f32 v[36:37], v[36:37], v[64:65], v[46:47] op_sel_hi:[0,1,1]
	v_mul_f32_e32 v36, v43, v67
	v_pk_fma_f32 v[64:65], v[42:43], v[66:67], v[36:37] op_sel_hi:[1,1,0] neg_lo:[0,0,1] neg_hi:[0,0,1]
	v_mul_f32_e32 v36, v43, v66
	v_pk_fma_f32 v[42:43], v[42:43], v[66:67], v[36:37] op_sel:[0,1,0] op_sel_hi:[1,0,0]
	v_pk_mul_f32 v[72:73], v[38:39], v[68:69] op_sel:[1,1] op_sel_hi:[1,0]
	v_mul_f32_e32 v36, v41, v71
	v_pk_mul_f32 v[66:67], v[38:39], v[68:69]
	v_pk_fma_f32 v[38:39], v[38:39], v[68:69], v[72:73] op_sel_hi:[0,1,1]
	v_pk_fma_f32 v[68:69], v[40:41], v[70:71], v[36:37] op_sel_hi:[1,1,0] neg_lo:[0,0,1] neg_hi:[0,0,1]
	v_mul_f32_e32 v36, v41, v70
	v_pk_fma_f32 v[40:41], v[40:41], v[70:71], v[36:37] op_sel:[0,1,0] op_sel_hi:[1,0,0]
	v_sub_f32_e32 v36, v34, v46
	v_sub_f32_e32 v38, v66, v72
	v_mov_b32_e32 v41, v40
	v_mov_b32_e32 v40, v68
	v_mov_b32_e32 v43, v42
	v_mov_b32_e32 v42, v64

; __device__ __forceinline__ unsigned pk2(float lo, float hi) { const f32x2_cv v = {lo, hi}; const bf16x2_cv b = __builtin_convertvector(v, bf16x2_cv); return __builtin_bit_cast(unsigned, b); }
;     __device__ __forceinline__ void operator()(const pg8::f32x4 (&acc)[2][2][4][2], const pg8::Unit& u, int wr, int wc, int fr, int fq) const {
;     ...
;                 for (int bj = 0; bj < 2; ++bj) {
;                     pg8::f32x4 y0 = acc[ai][bj][m][0], y1 = acc[ai][bj][m][1];
;                     if (normed) {
;                         y0 = y0 * rinv * gg[bj][0]; y1 = y1 * rinv * gg[bj][1];
;                         if (lat) { const int p = bj == 0 ? (t >> 6) : (t & 63); const pg8::f32x4* rp = (const pg8::f32x4*)(rope + p * 16 + 4 * fq); const pg8::f32x4 c01 = rp[0], c23 = rp[1];
;                             const pg8::f32x4 z0 = {y0[0] * c01[0] - y0[1] * c01[1], y0[0] * c01[1] + y0[1] * c01[0], y0[2] * c01[2] - y0[3] * c01[3], y0[2] * c01[3] + y0[3] * c01[2]};
;                             const pg8::f32x4 z1 = {y1[0] * c23[0] - y1[1] * c23[1], y1[0] * c23[1] + y1[1] * c23[0], y1[2] * c23[2] - y1[3] * c23[3], y1[2] * c23[3] + y1[3] * c23[2]};
;                             y0 = z0; y1 = z1; }
;                     }
;                     v4u o; o.x = pk2(y0[0], y0[1]); o.y = pk2(y0[2], y0[3]); o.z = pk2(y1[0], y1[1]); o.w = pk2(y1[2], y1[3]);
;                     *(v4u*)(dp + 32 * bj) = o;
.LBB0_443:
	v_and_b32_e32 v245, 63, v16
	v_mul_lo_u32 v30, v17, s94
	v_mul_lo_u32 v31, v16, s95
	v_mad_u64_u32 v[16:17], s[4:5], v16, s94, 0
	v_add3_u32 v17, v17, v31, v30
	v_lshl_add_u64 v[16:17], v[16:17], 1, v[160:161]
	v_mul_u32_u24_e32 v244, s100, v245
	v_and_b32_e32 v245, 1, v245
	v_mad_u32_u24 v244, v245, s101, v244
	v_sub_u32_e32 v244, 0, v244
	v_ashrrev_i32_e32 v245, 31, v244
	v_lshl_add_u64 v[16:17], v[16:17], 0, v[244:245]
	v_cvt_pk_bf16_f32 v20, v20, v21
	v_cvt_pk_bf16_f32 v21, v26, v27
	v_cvt_pk_bf16_f32 v22, v22, v23
	v_cvt_pk_bf16_f32 v23, v24, v25
	global_store_dwordx4 v[16:17], v[20:23], off
	s_and_b64 vcc, exec, s[38:39]
	v_mov_b32_e32 v26, v6
	v_mov_b32_e32 v20, v4
	v_mov_b32_e32 v21, v5
	v_mov_b32_e32 v27, v7
	v_mov_b32_e32 v22, v0
	v_mov_b32_e32 v23, v1
	v_mov_b32_e32 v24, v2
	v_mov_b32_e32 v25, v3
	s_cbranch_vccnz .LBB0_447
	v_mov_b32_e32 v22, v18
	v_mov_b32_e32 v23, v18
	v_pk_mul_f32 v[20:21], v[6:7], v[22:23]
	v_pk_mul_f32 v[24:25], v[4:5], v[18:19]
	v_pk_mul_f32 v[22:23], v[2:3], v[22:23]
	v_pk_mul_f32 v[18:19], v[0:1], v[18:19]
	s_waitcnt vmcnt(0)
	v_pk_mul_f32 v[26:27], v[54:55], v[20:21]
	v_pk_mul_f32 v[20:21], v[52:53], v[24:25]
	v_pk_mul_f32 v[24:25], v[50:51], v[22:23]
	v_pk_mul_f32 v[22:23], v[48:49], v[18:19]
	s_and_saveexec_b64 s[4:5], s[44:45]
	s_cbranch_execz .LBB0_446
	v_lshlrev_b32_e32 v18, 7, v29
	v_and_b32_e32 v18, 0x1f80, v18
	v_mov_b32_e32 v19, v209
	v_lshl_add_u64 v[18:19], v[154:155], 0, v[18:19]
	global_load_dwordx4 v[30:33], v[18:19], off
	global_load_dwordx4 v[34:37], v[18:19], off offset:16
	s_waitcnt vmcnt(0) lgkmcnt(0)
	v_pk_mul_f32 v[38:39], v[20:21], v[30:31] op_sel:[1,1] op_sel_hi:[1,0]
	v_pk_mul_f32 v[18:19], v[20:21], v[30:31]
	v_pk_fma_f32 v[20:21], v[20:21], v[30:31], v[38:39] op_sel_hi:[0,1,1]
	v_mul_f32_e32 v20, v27, v33
	v_pk_fma_f32 v[30:31], v[26:27], v[32:33], v[20:21] op_sel_hi:[1,1,0] neg_lo:[0,0,1] neg_hi:[0,0,1]
	v_mul_f32_e32 v20, v27, v32
	v_pk_fma_f32 v[26:27], v[26:27], v[32:33], v[20:21] op_sel:[0,1,0] op_sel_hi:[1,0,0]
	v_pk_mul_f32 v[40:41], v[22:23], v[34:35] op_sel:[1,1] op_sel_hi:[1,0]
	v_mul_f32_e32 v20, v25, v37
	v_pk_mul_f32 v[32:33], v[22:23], v[34:35]
	v_pk_fma_f32 v[22:23], v[22:23], v[34:35], v[40:41] op_sel_hi:[0,1,1]
	v_pk_fma_f32 v[34:35], v[24:25], v[36:37], v[20:21] op_sel_hi:[1,1,0] neg_lo:[0,0,1] neg_hi:[0,0,1]
	v_mul_f32_e32 v20, v25, v36
	v_pk_fma_f32 v[24:25], v[24:25], v[36:37], v[20:21] op_sel:[0,1,0] op_sel_hi:[1,0,0]
	v_sub_f32_e32 v20, v18, v38
	v_sub_f32_e32 v22, v32, v40
	v_mov_b32_e32 v25, v24
	v_mov_b32_e32 v24, v34
	v_mov_b32_e32 v27, v26
	v_mov_b32_e32 v26, v30

; __device__ __forceinline__ int lane_id_v() { int l; asm volatile("v_mbcnt_lo_u32_b32 %0, -1, 0\n\tv_mbcnt_hi_u32_b32 %0, -1, %0" : "=v"(l)); return l; }
;   #define DMA_K(t,slot) glds16(ksrc+(long)(t)*KVBLK*PK,(unsigned)__builtin_amdgcn_readfirstlane(kdst+(slot)))
;   #define DMA_V(t,slot) do{ glds16(vsrc+(long)(t)*KVBLK*PV,(unsigned)__builtin_amdgcn_readfirstlane(vdst+VS*(slot))); if constexpr(DV128){ glds16(vsrc+64+(long)(t)*KVBLK*PV,(unsigned)__builtin_amdgcn_readfirstlane(vdst+VS*(slot)+8192)); } }while(0)
; template<int THRL,bool DV128,int PQ,int PK,int PV,int PO> __device__ __forceinline__ void attn_unit(const bf16*Qb,const bf16*__restrict__ Kb,const bf16*__restrict__ Vb,bf16*Ob,const int NT,char*shm,const int wave0){
;   int tid_o=wave0*64+lane_id_v(); asm volatile("":"+v"(tid_o)); const int tid=tid_o,lane=tid&63,r32=lane&31,hi=lane>>5; const int wid=__builtin_amdgcn_readfirstlane(tid>>6);
;   const bf16*Qw=Qb+(long)(wid*QBLK)*PQ;
;   const bf16*Kh=Kb,*Vh=Vb;
;   const unsigned lds0=(unsigned)(uintptr_t)shm;
;   constexpr int VS=DV128?2:1, L_WS=LDS_V+NSLOT*SLOTB*VS, L_OST=L_WS+NW*64*4;
;   float*wsf=(float*)(shm+L_WS)+wid*64;
;   const bf16*ksrc=Kh+(long)lane*PK+wid*8;
;   const bf16*vsrc=Vh+(long)(16*(wid&3)+(lane>>2))*PV+(wid>>2)*32+(lane&3)*8;
;   const unsigned kdst=lds0+LDS_K+wid*1024, vdst=lds0+LDS_V+wid*1024;
;     ...
;   const char*Kbase=shm+LDS_K; bf16x8 kf[8];
;   const lds_cptr shm3=(lds_cptr)shm; const lds_cptr kp0=shm3+LDS_K+hi*1024+r32*16; const lds_cptr vp0=shm3+LDS_V+((lane>>4)&1)*32+(lane&3)*8+(4*hi+((lane&15)>>2))*64;
;   DMA_K(0,0);DMA_V(0,0);DMA_K(1,SLOTB);
;   bf16x8 qr[4];
;   #pragma unroll
;   for(int d0=0;d0<4;++d0)qr[d0]=*reinterpret_cast<const bf16x8*>(&Qw[(long)r32*PQ+d0*16+hi*8]);
.LBB0_719:
	s_bfe_u32 s35, s11, 0x20001
	s_lshl_b32 s5, s11, 7
	s_and_b32 s46, s11, 1
	s_mov_b64 s[6:7], s[58:59]
	s_lshl_b32 s66, s35, 1
	s_and_b32 s5, s5, 0x380
	s_add_u32 s12, s6, s5
	s_addc_u32 s13, s7, 0
	s_ashr_i32 s5, s4, 31
	s_lshl_b64 s[6:7], s[4:5], 10
	s_add_u32 s44, s12, s6
	s_addc_u32 s45, s13, s7
	s_and_b32 s67, s11, -8
	s_or_b32 s5, s66, s67
	s_or_b32 s5, s5, s46
	s_mov_b64 s[12:13], s[58:59]
	s_mul_hi_i32 s6, s5, 0x108000
	s_mul_i32 s5, s5, 0x108000
	s_add_u32 s36, s12, s5
	s_addc_u32 s37, s13, s6
	s_lshl_b32 s68, s10, 2
	s_mov_b64 s[14:15], s[58:59]
	s_or_b32 s5, s68, s35
	s_mov_b64 s[10:11], s[58:59]
	s_mul_hi_i32 s6, s5, 0x210000
	s_mul_i32 s5, s5, 0x210000
	v_mbcnt_lo_u32_b32 v0, -1, 0
	v_mbcnt_hi_u32_b32 v0, -1, v0
	s_add_u32 s40, s14, s5
	v_add_u32_e32 v60, s89, v0
	s_addc_u32 s41, s15, s6
	v_readfirstlane_b32 s69, v60
	s_ashr_i32 s5, s69, 6
	s_lshl_b32 s6, s5, 5
	s_ashr_i32 s7, s6, 31
	v_and_b32_e32 v243, 63, v60
	s_lshl_b64 s[42:43], s[6:7], 10
	s_add_u32 s42, s44, s42
	v_lshlrev_b32_e32 v208, 4, v243
	s_addc_u32 s43, s45, s43
	v_lshl_add_u64 v[0:1], s[36:37], 0, v[208:209]
	s_lshl_b32 s36, s5, 9
	s_ashr_i32 s37, s36, 31
	v_lshl_add_u64 v[48:49], s[36:37], 1, v[0:1]
	s_mov_b64 s[44:45], 0x17c00000
	v_lshl_add_u64 v[0:1], v[48:49], 0, s[44:45]
	s_lshl_b32 s44, s5, 4
	v_bfe_u32 v216, v60, 3, 3
	v_lshlrev_b32_e32 v2, 8, v216
	v_lshl_add_u32 v2, s5, 11, v2
	v_mov_b32_e32 v3, v209
	v_lshl_add_u64 v[2:3], s[40:41], 0, v[2:3]
	s_ashr_i32 s40, s69, 3
	s_mov_b32 s40, 0
	v_lshlrev_b32_e32 v246, 3, v60
	s_ashr_i32 s41, s40, 31
	v_and_b32_e32 v61, 24, v246
	s_and_b32 s7, s69, 0x3fffffc0
	v_lshl_add_u64 v[2:3], s[40:41], 1, v[2:3]
	v_and_b32_e32 v4, 56, v246
	v_lshlrev_b32_e32 v4, 1, v4
	v_mov_b32_e32 v5, v209
	s_lshl_b32 s49, s5, 10
	v_lshl_add_u64 v[50:51], v[2:3], 0, v[4:5]
	s_mov_b64 s[44:45], 0x19d00000
	s_cmp_lg_u32 0, -1
	v_lshl_add_u64 v[2:3], v[50:51], 0, s[44:45]
	s_cselect_b32 s44, 0, 0
	s_add_i32 s49, s49, s44
	s_mov_b32 s44, m0
	s_mov_b32 m0, s49
	s_nop 0
	global_load_lds_dwordx4 v[0:1], off
	s_mov_b32 m0, s44
	s_add_i32 s60, s49, 0x6000
	s_mov_b32 s44, m0
	s_mov_b32 m0, s60
	s_nop 0
	global_load_lds_dwordx4 v[2:3], off
	s_mov_b32 m0, s44
	s_mov_b64 s[44:45], 0x19d00080
	v_lshl_add_u64 v[0:1], v[50:51], 0, s[44:45]
	s_add_i32 s44, s49, 0x8000
	s_mov_b32 s45, m0
	s_mov_b32 m0, s44
	s_nop 0
	global_load_lds_dwordx4 v[0:1], off
	s_mov_b32 m0, s45
	s_mov_b64 s[44:45], 0x17c02000
	v_and_b32_e32 v244, 31, v60
	v_lshl_add_u64 v[0:1], v[48:49], 0, s[44:45]
	v_bfe_u32 v245, v60, 5, 1
	s_add_i32 s44, s49, 0x2000
	s_mov_b32 s45, m0
	s_mov_b32 m0, s44
	s_nop 0
	global_load_lds_dwordx4 v[0:1], off
	s_mov_b32 m0, s45
	v_lshlrev_b32_e32 v0, 10, v244
	v_lshl_or_b32 v0, v245, 4, v0
	v_mov_b32_e32 v1, v209
	v_lshl_add_u64 v[0:1], s[42:43], 0, v[0:1]
	s_mov_b32 s42, 0x15b00000
	v_add_co_u32_e32 v2, vcc, s42, v0
	s_mov_b64 s[42:43], 0x15b00000
	s_nop 0
	v_addc_co_u32_e32 v3, vcc, 0, v1, vcc
	global_load_dwordx4 v[172:175], v[2:3], off
	v_lshl_add_u64 v[0:1], v[0:1], 0, s[42:43]
	global_load_dwordx4 v[168:171], v[0:1], off offset:32
	global_load_dwordx4 v[164:167], v[0:1], off offset:64
	global_load_dwordx4 v[156:159], v[0:1], off offset:96
	v_lshlrev_b32_e32 v2, 10, v245
	v_lshlrev_b32_e32 v3, 4, v244
	v_mov_b32_e32 v14, v209
	v_mov_b32_e32 v15, v209
	v_add3_u32 v250, 0, v2, v3
	v_mov_b32_e32 v0, v209
	v_mov_b32_e32 v1, v209
	v_mov_b32_e32 v2, v209
	v_mov_b32_e32 v3, v209
	v_mov_b32_e32 v4, v209
	v_mov_b32_e32 v6, v209
	v_mov_b32_e32 v7, v209
	v_mov_b32_e32 v8, v209
	v_mov_b32_e32 v9, v209
	v_mov_b32_e32 v10, v209
	v_mov_b32_e32 v11, v209
	v_mov_b32_e32 v12, v209
	v_mov_b32_e32 v13, v209
	v_mov_b64_e32 v[30:31], v[14:15]
	v_mov_b64_e32 v[28:29], v[12:13]
	v_mov_b64_e32 v[26:27], v[10:11]
	v_mov_b64_e32 v[24:25], v[8:9]
	v_mov_b64_e32 v[22:23], v[6:7]
	v_mov_b64_e32 v[20:21], v[4:5]
	v_mov_b64_e32 v[18:19], v[2:3]
	v_mov_b64_e32 v[16:17], v[0:1]
	s_mov_b64 s[42:43], 0x17c04000
	v_lshl_add_u64 v[32:33], v[48:49], 0, s[42:43]
	s_add_i32 s42, s49, 0x4000
	s_mov_b32 s43, m0
	s_mov_b32 m0, s42
	s_nop 0
	global_load_lds_dwordx4 v[32:33], off
	s_mov_b32 m0, s43
	s_waitcnt vmcnt(3) lgkmcnt(0)
	s_barrier
	ds_read_b128 v[52:55], v250
	ds_read_b128 v[56:59], v250 offset:512
	s_waitcnt vmcnt(0) lgkmcnt(0)
	v_mfma_f32_32x32x16_bf16 v[32:47], v[52:55], v[172:175], v[16:31]
	s_mov_b64 s[70:71], 0x17c06000
	v_lshlrev_b32_e32 v62, 1, v60
	s_lshl_b32 s7, s7, 2
	s_add_i32 s7, s7, 0
	s_add_i32 s7, s7, 0x12000
	s_mov_b32 s42, 1
	s_mov_b32 s61, 0
	v_mfma_f32_32x32x16_bf16 v[16:31], v[56:59], v[172:175], v[16:31]
	ds_read_b128 v[52:55], v250 offset:2048
	ds_read_b128 v[56:59], v250 offset:2560
	s_movk_i32 s65, 0x2000
	s_movk_i32 s44, 0x4000
	s_andn2_b64 vcc, exec, s[38:39]
	v_cmp_gt_u32_e64 s[38:39], 32, v243
	v_lshlrev_b32_e32 v251, 4, v245
	v_lshl_add_u32 v247, v244, 2, s7
	s_waitcnt lgkmcnt(1)
	v_mfma_f32_32x32x16_bf16 v[32:47], v[52:55], v[168:171], v[32:47]
	s_waitcnt lgkmcnt(0)
	v_mfma_f32_32x32x16_bf16 v[16:31], v[56:59], v[168:171], v[16:31]
	ds_read_b128 v[52:55], v250 offset:4096
	ds_read_b128 v[56:59], v250 offset:4608
	s_waitcnt lgkmcnt(1)
	v_mfma_f32_32x32x16_bf16 v[32:47], v[52:55], v[164:167], v[32:47]
	s_waitcnt lgkmcnt(0)
	v_mfma_f32_32x32x16_bf16 v[16:31], v[56:59], v[164:167], v[16:31]
	ds_read_b128 v[52:55], v250 offset:6144
	ds_read_b128 v[56:59], v250 offset:6656
	s_waitcnt lgkmcnt(1)
	v_mfma_f32_32x32x16_bf16 v[32:47], v[52:55], v[156:159], v[32:47]
	v_and_b32_e32 v52, 32, v62
	v_lshlrev_b32_e32 v54, 4, v60
	v_add3_u32 v52, 0, v52, v61
	v_lshlrev_b32_e32 v53, 8, v245
	v_and_b32_e32 v54, 0xc0, v54
	v_add3_u32 v248, v52, v53, v54
	s_waitcnt lgkmcnt(0)
; #define WAIT_BAR(N) asm volatile("s_waitcnt vmcnt(" #N ") lgkmcnt(0)\n\ts_barrier":::"memory")
;   #define DMA_K(t,slot) glds16(ksrc+(long)(t)*KVBLK*PK,(unsigned)__builtin_amdgcn_readfirstlane(kdst+(slot)))
;   #define DMA_V(t,slot) do{ glds16(vsrc+(long)(t)*KVBLK*PV,(unsigned)__builtin_amdgcn_readfirstlane(vdst+VS*(slot))); if constexpr(DV128){ glds16(vsrc+64+(long)(t)*KVBLK*PV,(unsigned)__builtin_amdgcn_readfirstlane(vdst+VS*(slot)+8192)); } }while(0)
;   #define CMASK(P0,P1,t) do{}while(0)
;   #define START(P0,P1) do{ const float rm=rowmax(P0,P1); resc=false; \
;     { const float dl=rm; mhat=fadd_s(mhat,dl); \
;       _Pragma("unroll") for(int r=0;r<16;++r){P0[r]=fsub_s(P0[r],dl);P1[r]=fsub_s(P1[r],dl);} \
;       _Pragma("unroll") for(int r=0;r<16;++r)negm[r]=-mhat; asm volatile("":"+v"(negm)); } \
;     _Pragma("unroll") for(int r=0;r<16;++r)P0[r]=__builtin_amdgcn_exp2f(P0[r]); }while(0)
;   #define ROT() do{sl_prev=sl_cur;sl_cur=sl_next;sl_next=(sl_next==(NSLOT-1)*SLOTB)?0:sl_next+SLOTB;}while(0)
;   #define WB2() do{ if constexpr(DV128){WAIT_BAR(3);}else{WAIT_BAR(2);} }while(0)
;   #define CMASK(P0,P1,t) do{}while(0)
;   #define CMASK(P0,P1,t) do{}while(0)
; template<int THRL,bool DV128,int PQ,int PK,int PV,int PO> __device__ __forceinline__ void attn_unit(const bf16*Qb,const bf16*__restrict__ Kb,const bf16*__restrict__ Vb,bf16*Ob,const int NT,char*shm,const int wave0){
;     ...
;   DMA_K(2,2*SLOTB);
;   WAIT_BAR(3);
;   qkt(pA0,pA1,Kbase,qr,negm,r32,hi);asm volatile("s_nop 15\n\ts_nop 7":"+v"(pA0),"+v"(pA1));CMASK(pA0,pA1,0);
;   START(pA0,pA1);
;   _Pragma("unroll") for(int r=0;r<16;++r)pA1[r]=__builtin_amdgcn_exp2f(pA1[r]);
;   WAIT_BAR(0);
;   DMA_K(3,0);DMA_V(1,SLOTB);
;   ROT();
;   kload8(kf,kp0+sl_cur);
;     ...
;   WB2();
;   s16x4 vlo[8],vhi[8]; u32x4 pw0,pw1,pw2,pw3;
	v_mfma_f32_32x32x16_bf16 v[16:31], v[56:59], v[156:159], v[16:31]
	s_nop 15
	s_nop 7
	s_nop 0
	v_max3_f32 v55, v32, v33, v16
	v_max3_f32 v56, v34, v35, v17
	s_nop 0
	v_max3_f32 v55, v55, v18, v19
	v_max3_f32 v56, v56, v38, v39
	s_nop 0
	v_max3_f32 v55, v55, v36, v37
	v_max3_f32 v56, v56, v22, v23
	s_nop 0
	v_max3_f32 v55, v55, v20, v21
	v_max3_f32 v56, v56, v42, v43
	s_nop 0
	v_max3_f32 v55, v55, v40, v41
	v_max3_f32 v56, v56, v26, v27
	s_nop 0
	v_max3_f32 v55, v55, v24, v25
	v_max3_f32 v56, v56, v46, v47
	s_nop 0
	v_max3_f32 v55, v55, v44, v45
	v_max3_f32 v56, v56, v30, v31
	s_nop 0
	v_max3_f32 v55, v55, v28, v29
	s_nop 0
	v_max_f32_e32 v55, v55, v56
	s_nop 0
	v_mov_b32_e32 v56, v55
	s_nop 1
	v_permlane32_swap_b32_e32 v55, v56
	v_max_f32_e32 v55, v55, v56
	s_nop 0
	v_add_f32_e32 v249, v209, v55
	v_sub_f32_e32 v16, v16, v55
	v_sub_f32_e32 v17, v17, v55
	v_sub_f32_e32 v32, v32, v55
	v_sub_f32_e32 v33, v33, v55
	v_sub_f32_e32 v34, v34, v55
	s_nop 0
	v_xor_b32_e32 v64, 0x80000000, v249
	v_mov_b32_e32 v65, v64
	v_mov_b32_e32 v66, v64
	v_mov_b32_e32 v67, v64
	v_mov_b32_e32 v68, v64
	v_mov_b32_e32 v69, v64
	v_mov_b32_e32 v70, v64
	v_mov_b32_e32 v71, v64
	v_mov_b32_e32 v72, v64
	v_mov_b32_e32 v73, v64
	v_mov_b32_e32 v74, v64
	v_mov_b32_e32 v75, v64
	v_mov_b32_e32 v76, v64
	v_mov_b32_e32 v77, v64
	v_mov_b32_e32 v78, v64
	v_mov_b32_e32 v79, v64
	s_waitcnt vmcnt(0) lgkmcnt(0)
	s_barrier
	v_exp_f32_e32 v80, v16
	v_exp_f32_e32 v81, v17
	v_lshl_add_u64 v[16:17], v[48:49], 0, s[70:71]
	s_mov_b32 s43, m0
	s_mov_b32 m0, s49
	s_nop 0
	global_load_lds_dwordx4 v[16:17], off
	s_mov_b32 m0, s43
	s_mov_b64 s[70:71], 0x19d04000
	v_lshl_add_u64 v[16:17], v[50:51], 0, s[70:71]
	s_add_i32 s43, s49, 0xa000
	s_mov_b32 s45, m0
	s_mov_b32 m0, s43
	s_nop 0
	global_load_lds_dwordx4 v[16:17], off
	s_mov_b32 m0, s45
	s_mov_b64 s[70:71], 0x19d04080
	v_lshl_add_u64 v[16:17], v[50:51], 0, s[70:71]
	s_add_i32 s43, s49, 0xc000
	s_mov_b32 s45, m0
	s_mov_b32 m0, s43
	s_nop 0
	global_load_lds_dwordx4 v[16:17], off
	s_mov_b32 m0, s45
	ds_read_b128 v[204:207], v250 offset:8192
	ds_read_b128 v[200:203], v250 offset:8704
	ds_read_b128 v[196:199], v250 offset:10240
	ds_read_b128 v[192:195], v250 offset:10752
	ds_read_b128 v[188:191], v250 offset:12288
	ds_read_b128 v[184:187], v250 offset:12800
	ds_read_b128 v[180:183], v250 offset:14336
	ds_read_b128 v[176:179], v250 offset:14848
	v_sub_f32_e32 v18, v18, v55
	v_sub_f32_e32 v35, v35, v55
	v_sub_f32_e32 v19, v19, v55
	v_sub_f32_e32 v36, v36, v55
	v_sub_f32_e32 v20, v20, v55
	v_sub_f32_e32 v37, v37, v55
	v_sub_f32_e32 v21, v21, v55
	v_sub_f32_e32 v38, v38, v55
	v_sub_f32_e32 v22, v22, v55
	v_sub_f32_e32 v39, v39, v55
	v_sub_f32_e32 v23, v23, v55
	v_sub_f32_e32 v40, v40, v55
	v_sub_f32_e32 v24, v24, v55
	v_sub_f32_e32 v41, v41, v55
	v_sub_f32_e32 v25, v25, v55
	v_sub_f32_e32 v42, v42, v55
	v_sub_f32_e32 v26, v26, v55
	v_sub_f32_e32 v43, v43, v55
	v_sub_f32_e32 v27, v27, v55
	v_sub_f32_e32 v44, v44, v55
	v_sub_f32_e32 v28, v28, v55
	v_sub_f32_e32 v45, v45, v55
	v_sub_f32_e32 v29, v29, v55
	v_sub_f32_e32 v46, v46, v55
	v_sub_f32_e32 v30, v30, v55
	v_sub_f32_e32 v47, v47, v55
	v_sub_f32_e32 v31, v31, v55
	v_exp_f32_e32 v96, v32
	v_exp_f32_e32 v97, v33
	v_exp_f32_e32 v98, v34
	v_exp_f32_e32 v99, v35
	v_exp_f32_e32 v100, v36
	v_exp_f32_e32 v101, v37
	v_exp_f32_e32 v102, v38
	v_exp_f32_e32 v103, v39
	v_exp_f32_e32 v104, v40
	v_exp_f32_e32 v105, v41
	v_exp_f32_e32 v106, v42
	v_exp_f32_e32 v107, v43
	v_exp_f32_e32 v108, v44
	v_exp_f32_e32 v109, v45
	v_exp_f32_e32 v110, v46
	v_exp_f32_e32 v111, v47
	v_exp_f32_e32 v82, v18
	v_exp_f32_e32 v83, v19
	v_exp_f32_e32 v84, v20
	v_exp_f32_e32 v85, v21
	v_exp_f32_e32 v86, v22
	v_exp_f32_e32 v87, v23
	v_exp_f32_e32 v88, v24
	v_exp_f32_e32 v89, v25
	v_exp_f32_e32 v90, v26
	v_exp_f32_e32 v91, v27
	v_exp_f32_e32 v92, v28
	v_exp_f32_e32 v93, v29
	v_exp_f32_e32 v94, v30
	v_exp_f32_e32 v95, v31
	s_waitcnt vmcnt(3) lgkmcnt(0)
	s_barrier
	v_and_b32_e32 v16, 7, v60
	v_lshlrev_b32_e32 v210, 4, v16
	s_cbranch_vccnz .LBB0_735
	s_add_i32 s42, s68, s35
	s_mul_hi_i32 s44, s42, 0x210000
	s_mul_i32 s45, s42, 0x210000
	s_lshl_b64 s[42:43], s[40:41], 1
	s_add_u32 s42, s42, s45
	v_mov_b32_e32 v211, v209
	s_addc_u32 s43, s43, s44
	v_lshl_add_u64 v[0:1], s[42:43], 0, v[210:211]
	s_lshl_b32 s42, s69, 5
	s_nop 0
	v_lshl_or_b32 v2, v216, 8, s42
	v_mov_b32_e32 v3, v209
	v_lshl_add_u64 v[0:1], v[0:1], 0, v[2:3]
	v_lshl_add_u64 v[0:1], s[14:15], 0, v[0:1]
	s_mov_b64 s[42:43], 0x19d0c080
	v_lshl_add_u64 v[212:213], v[0:1], 0, s[42:43]
	s_add_i32 s42, s67, s66
	s_add_i32 s42, s42, s46
	s_mul_hi_i32 s44, s42, 0x108000
	s_mul_i32 s45, s42, 0x108000
	s_lshl_b64 s[42:43], s[36:37], 1
	s_add_u32 s42, s12, s42
	s_addc_u32 s43, s13, s43
	s_add_u32 s42, s42, s45
	s_addc_u32 s43, s43, s44
	v_lshl_add_u64 v[0:1], s[42:43], 0, v[208:209]
	s_mov_b64 s[42:43], 0x17c0a000
	v_mov_b32_e32 v32, v209
	v_mov_b32_e32 v33, v209
	v_mov_b32_e32 v46, v209
	v_mov_b32_e32 v47, v209
	v_lshl_add_u64 v[214:215], v[0:1], 0, s[42:43]
	v_mov_b32_e32 v34, v209
	v_mov_b32_e32 v35, v209
	v_mov_b32_e32 v36, v209
	v_mov_b32_e32 v37, v209
	v_mov_b32_e32 v38, v209
	v_mov_b32_e32 v39, v209
	v_mov_b32_e32 v40, v209
	v_mov_b32_e32 v41, v209
	v_mov_b32_e32 v42, v209
	v_mov_b32_e32 v43, v209
	v_mov_b32_e32 v44, v209
	v_mov_b32_e32 v45, v209
	v_mov_b64_e32 v[62:63], v[46:47]
	v_mov_b64_e32 v[16:17], v[32:33]
	v_mov_b64_e32 v[0:1], v[32:33]
	s_mov_b32 s70, 6
	s_mov_b32 s72, 0
	s_movk_i32 s61, 0x4000
	s_movk_i32 s71, 0x2000
	v_mov_b32_e32 v252, 0
	v_mov_b64_e32 v[60:61], v[44:45]
	v_mov_b64_e32 v[58:59], v[42:43]
	v_mov_b64_e32 v[56:57], v[40:41]
	v_mov_b64_e32 v[54:55], v[38:39]
	v_mov_b64_e32 v[52:53], v[36:37]
	v_mov_b64_e32 v[50:51], v[34:35]
	v_mov_b64_e32 v[48:49], v[32:33]
	v_mov_b64_e32 v[18:19], v[34:35]
	v_mov_b64_e32 v[20:21], v[36:37]
	v_mov_b64_e32 v[22:23], v[38:39]
	v_mov_b64_e32 v[24:25], v[40:41]
	v_mov_b64_e32 v[26:27], v[42:43]
	v_mov_b64_e32 v[28:29], v[44:45]
	v_mov_b64_e32 v[30:31], v[46:47]
	v_mov_b64_e32 v[2:3], v[34:35]
	v_mov_b64_e32 v[4:5], v[36:37]
	v_mov_b64_e32 v[6:7], v[38:39]
	v_mov_b64_e32 v[8:9], v[40:41]
	v_mov_b64_e32 v[10:11], v[42:43]
	v_mov_b64_e32 v[12:13], v[44:45]
	v_mov_b64_e32 v[14:15], v[46:47]

;   #define RESC() do{ if(resc){ asm volatile("s_waitcnt lgkmcnt(0)":::"memory"); \
;       _Pragma("unroll") for(int d_=0;d_<2*VS;++d_) _Pragma("unroll") for(int r=0;r<16;++r)o[d_][r]*=wsf[crow(r,hi)]; } }while(0)
;   #define ROT() do{sl_prev=sl_cur;sl_cur=sl_next;sl_next=(sl_next==(NSLOT-1)*SLOTB)?0:sl_next+SLOTB;}while(0)
;   #define STEPX(...) do{ if constexpr(DV128){ STEP128(__VA_ARGS__); } else { STEP(__VA_ARGS__); } }while(0)
;   #define ENDW(tt) do{ if((tt)+3<NT){WB2();} else if((tt)+2<NT){WB1();} else {WAIT_BAR(0);} }while(0)
; template<int THRL,bool DV128,int PQ,int PK,int PV,int PO> __device__ __forceinline__ void attn_unit(const bf16*Qb,const bf16*__restrict__ Kb,const bf16*__restrict__ Vb,bf16*Ob,const int NT,char*shm,const int wave0){
;     ...
;   const bf16*vsrc=Vh+(long)(16*(wid&3)+(lane>>2))*PV+(wid>>2)*32+(lane&3)*8;
;   const unsigned kdst=lds0+LDS_K+wid*1024, vdst=lds0+LDS_V+wid*1024;
;     ...
;   for(;t+1<NT;t+=2){
;     STEPX(pB0,pB1,pA0,pA1,t,(t+3<NT),(t+1<NT),(t+1<NT));       ENDW(t);   RESC(); ROT();
;     STEPX(pA0,pA1,pB0,pB1,t+1,(t+4<NT),(t+2<NT),(t+2<NT));     ENDW(t+1); RESC(); ROT();
.LBB0_738:
	s_andn2_b64 vcc, exec, s[38:39]
	s_cbranch_vccnz .LBB0_784
	s_add_i32 s43, s68, s35
	s_mul_hi_i32 s45, s43, 0x210000
	s_mul_i32 s68, s43, 0x210000
	s_mov_b32 s43, s64
	s_add_i32 s70, s47, -2
	s_lshl_b64 s[72:73], s[42:43], 14
	s_add_u32 s68, s68, s72
	s_addc_u32 s45, s45, s73
	s_lshl_b64 s[40:41], s[40:41], 1
	s_add_u32 s40, s40, s68
	v_mov_b32_e32 v211, v209
	s_addc_u32 s41, s41, s45
	v_lshl_add_u64 v[112:113], s[40:41], 0, v[210:211]
	s_lshl_b32 s40, s69, 5
	s_nop 0
	v_lshl_or_b32 v114, v216, 8, s40
	v_mov_b32_e32 v115, v209
	v_lshl_add_u64 v[112:113], v[112:113], 0, v[114:115]
	v_lshl_add_u64 v[112:113], s[14:15], 0, v[112:113]
	s_mov_b64 s[14:15], 0x19d04000
	v_lshl_add_u64 v[210:211], v[112:113], 0, s[14:15]
	s_add_i32 s14, s67, s66
	s_add_i32 s14, s14, s46
	s_add_i32 s40, s42, 2
	s_mul_hi_i32 s41, s14, 0x108000
	s_mul_i32 s45, s14, 0x108000
	s_lshl_b64 s[14:15], s[42:43], 13
	s_add_u32 s42, s45, s14
	s_addc_u32 s41, s41, s15
	s_lshl_b64 s[14:15], s[36:37], 1
	s_add_u32 s12, s12, s14
	s_addc_u32 s13, s13, s15
	s_add_u32 s12, s12, s42
	s_addc_u32 s13, s13, s41
	v_lshl_add_u64 v[112:113], s[12:13], 0, v[208:209]
	s_mov_b64 s[12:13], 0x17c08000
	v_cmp_gt_u32_e64 s[38:39], 32, v243
	s_movk_i32 s72, 0x3000
	v_lshl_add_u64 v[212:213], v[112:113], 0, s[12:13]
	v_mov_b32_e32 v216, v238
